# PEER selection of the block's shared 9th token split by heads across the 4 waves (2 heads each, results published to all waves' LDS tables + block barrier)
# speedup vs baseline: 1.0062x; 1.0062x over previous
.LBB0_1113:
	s_cmp_lt_i32 s92, 10
	s_cselect_b64 s[0:1], -1, 0
	s_cmp_gt_i32 s93, 9
	s_cselect_b64 s[4:5], -1, 0
	s_and_b64 s[0:1], s[0:1], s[4:5]
	s_andn2_b64 vcc, exec, s[0:1]
	s_cbranch_vccnz .LBB0_1592
	v_lshl_add_u32 v96, s2, 2, v214
	s_movk_i32 s0, 0x4200
	v_cmp_gt_i32_e32 vcc, s0, v96
	s_and_saveexec_b64 s[28:29], vcc
	s_cbranch_execz .LBB0_1538
	s_waitcnt vmcnt(25)
	v_mbcnt_lo_u32_b32 v6, -1, 0
	v_mbcnt_hi_u32_b32 v6, -1, v6
	v_and_b32_e32 v7, 64, v6
	v_add_u32_e32 v7, 64, v7
	v_xor_b32_e32 v8, 32, v6
	v_cmp_lt_i32_e64 s[0:1], v8, v7
	v_and_b32_e32 v4, 63, v218
	v_add_u32_e32 v0, -16, v4
	v_cndmask_b32_e64 v8, v6, v8, s[0:1]
	v_lshlrev_b32_e32 v137, 2, v8
	v_xor_b32_e32 v8, 16, v6
	v_cmp_lt_i32_e64 s[0:1], v8, v7
	v_min_u32_e32 v0, v0, v4
	v_subrev_co_u32_e32 v1, vcc, 24, v4
	v_cndmask_b32_e64 v8, v6, v8, s[0:1]
	v_lshlrev_b32_e32 v138, 2, v8
	v_xor_b32_e32 v8, 8, v6
	v_cmp_lt_i32_e64 s[0:1], v8, v7
	v_cndmask_b32_e32 v0, v1, v0, vcc
	v_subrev_co_u32_e64 v1, s[18:19], 29, v4
	v_cndmask_b32_e64 v8, v6, v8, s[0:1]
	v_lshlrev_b32_e32 v139, 2, v8
	v_xor_b32_e32 v8, 4, v6
	v_cmp_lt_i32_e64 s[0:1], v8, v7
	v_mul_u32_u24_e32 v136, 0x500, v214
	v_cndmask_b32_e64 v0, v1, v0, s[18:19]
	v_cndmask_b32_e64 v8, v6, v8, s[0:1]
	v_lshlrev_b32_e32 v140, 2, v8
	v_xor_b32_e32 v8, 2, v6
	v_cmp_lt_i32_e64 s[0:1], v8, v7
	v_subrev_co_u32_e64 v1, s[20:21], 33, v4
	s_nop 0
	v_cndmask_b32_e64 v8, v6, v8, s[0:1]
	v_lshlrev_b32_e32 v141, 2, v8
	v_xor_b32_e32 v8, 1, v6
	v_cmp_lt_i32_e64 s[0:1], v8, v7
	v_and_b32_e32 v7, 58, v218
	v_cndmask_b32_e64 v0, v1, v0, s[20:21]
	v_cndmask_b32_e64 v6, v6, v8, s[0:1]
	v_cmp_ne_u32_e64 s[0:1], 0, v4
	v_lshlrev_b32_e32 v142, 2, v6
	v_and_b32_e32 v6, 1, v218
	v_cndmask_b32_e64 v144, 0, 1, s[0:1]
	v_cmp_lt_u32_e64 s[0:1], 1, v4
	v_cmp_eq_u32_e64 s[6:7], 0, v6
	v_and_b32_e32 v6, 2, v218
	v_cndmask_b32_e64 v145, 0, 1, s[0:1]
	v_cmp_lt_u32_e64 s[0:1], 2, v4
	v_lshlrev_b32_e32 v8, 4, v218
	v_subrev_co_u32_e64 v1, s[22:23], 36, v4
	v_cndmask_b32_e64 v146, 0, 1, s[0:1]
	v_cmp_lt_u32_e64 s[0:1], 3, v4
	v_cmp_eq_u32_e64 s[8:9], 0, v6
	v_and_b32_e32 v6, 4, v218
	v_cndmask_b32_e64 v147, 0, 1, s[0:1]
	v_cmp_lt_u32_e64 s[0:1], 4, v4
	v_and_or_b32 v8, v8, 16, v136
	v_lshlrev_b32_e32 v7, 2, v7
	v_cndmask_b32_e64 v148, 0, 1, s[0:1]
	v_cmp_lt_u32_e64 s[0:1], 5, v4
	v_cndmask_b32_e64 v0, v1, v0, s[22:23]
	v_subrev_co_u32_e64 v1, s[26:27], 38, v4
	v_cndmask_b32_e64 v149, 0, 1, s[0:1]
	v_cmp_lt_u32_e64 s[0:1], 6, v4
	v_cmp_eq_u32_e64 s[10:11], 0, v6
	v_or3_b32 v195, v8, v7, v6
	v_cndmask_b32_e64 v150, 0, 1, s[0:1]
	v_cmp_lt_u32_e64 s[0:1], 7, v4
	v_cndmask_b32_e64 v2, v1, v0, s[26:27]
	v_subrev_co_u32_e64 v3, s[24:25], 40, v4
	v_cndmask_b32_e64 v151, 0, 1, s[0:1]
	v_cmp_lt_u32_e64 s[0:1], 8, v4
	v_subrev_u32_e32 v0, 34, v4
	v_cmp_gt_u32_e64 s[4:5], 50, v4
	v_cndmask_b32_e64 v152, 0, 1, s[0:1]
	v_cmp_lt_u32_e64 s[0:1], 9, v4
	v_readlane_b32 s36, v242, 25
	v_cndmask_b32_e64 v5, 0, v0, s[4:5]
	v_cndmask_b32_e64 v153, 0, 1, s[0:1]
	v_cmp_lt_u32_e64 s[0:1], 10, v4
	v_lshlrev_b32_e32 v0, 4, v4
	v_mov_b32_e32 v1, 0
	v_cndmask_b32_e64 v154, 0, 1, s[0:1]
	v_cmp_lt_u32_e64 s[0:1], 11, v4
	v_readlane_b32 s38, v242, 27
	v_readlane_b32 s39, v242, 28
	v_cndmask_b32_e64 v155, 0, 1, s[0:1]
	v_cmp_lt_u32_e64 s[0:1], 12, v4
	v_lshl_add_u64 v[106:107], s[38:39], 0, v[0:1]
	v_lshlrev_b32_e32 v0, 5, v4
	v_cndmask_b32_e64 v156, 0, 1, s[0:1]
	v_cmp_lt_u32_e64 s[0:1], 13, v4
	v_mov_b32_e32 v101, v1
	v_mov_b32_e32 v99, v1
	v_cndmask_b32_e64 v157, 0, 1, s[0:1]
	v_cmp_lt_u32_e64 s[0:1], 14, v4
	v_lshl_add_u64 v[110:111], s[82:83], 0, v[0:1]
	v_readlane_b32 s64, v242, 1
	v_cndmask_b32_e64 v158, 0, 1, s[0:1]
	v_cmp_lt_u32_e64 s[0:1], 15, v4
	v_readlane_b32 s65, v242, 2
	v_readlane_b32 s66, v242, 3
	v_cndmask_b32_e64 v159, 0, 1, s[0:1]
	v_cmp_lt_u32_e64 s[0:1], 16, v4
	v_cndmask_b32_e32 v6, 2, v159, vcc
	v_cndmask_b32_e64 v6, 3, v6, s[18:19]
	v_cndmask_b32_e64 v160, 0, 1, s[0:1]
	v_cmp_lt_u32_e64 s[0:1], 17, v4
	v_cmp_gt_u32_e32 vcc, 42, v4
	v_cndmask_b32_e64 v6, 4, v6, s[20:21]
	v_cndmask_b32_e64 v161, 0, 1, s[0:1]
	v_cmp_lt_u32_e64 s[0:1], 18, v4
	v_cndmask_b32_e32 v3, 0, v3, vcc
	v_cndmask_b32_e64 v6, 5, v6, s[22:23]
	s_waitcnt vmcnt(18)
	v_cndmask_b32_e64 v162, 0, 1, s[0:1]
	v_cmp_lt_u32_e64 s[0:1], 19, v4
	v_cndmask_b32_e64 v98, v3, v2, s[24:25]
	v_cndmask_b32_e64 v6, 6, v6, s[26:27]
	v_cndmask_b32_e64 v163, 0, 1, s[0:1]
	v_cmp_lt_u32_e64 s[0:1], 20, v4
	v_cndmask_b32_e64 v5, v5, 7, vcc
	v_mov_b32_e32 v3, v1
	v_cndmask_b32_e64 v164, 0, 1, s[0:1]
	v_cmp_lt_u32_e64 s[0:1], 21, v4
	v_ashrrev_i32_e32 v1, 31, v98
	v_mov_b32_e32 v0, v98
	v_cndmask_b32_e64 v165, 0, 1, s[0:1]
	v_cmp_lt_u32_e64 s[0:1], 22, v4
	v_cndmask_b32_e64 v100, v5, v6, s[24:25]
	v_lshl_add_u64 v[0:1], v[0:1], 2, s[84:85]
	s_waitcnt vmcnt(6)
	v_cndmask_b32_e64 v166, 0, 1, s[0:1]
	v_cmp_lt_u32_e64 s[0:1], 23, v4
	v_lshlrev_b32_e32 v2, 6, v4
	v_readlane_b32 s67, v242, 4
	v_cndmask_b32_e64 v167, 0, 1, s[0:1]
	v_cmp_lt_u32_e64 s[0:1], 24, v4
	v_readlane_b32 s68, v242, 5
	v_readlane_b32 s69, v242, 6
	v_cndmask_b32_e64 v168, 0, 1, s[0:1]
	v_cmp_lt_u32_e64 s[0:1], 25, v4
	v_readlane_b32 s70, v242, 7
	v_readlane_b32 s71, v242, 8
	v_cndmask_b32_e64 v169, 0, 1, s[0:1]
	v_cmp_lt_u32_e64 s[0:1], 26, v4
	v_readlane_b32 s72, v242, 9
	v_readlane_b32 s73, v242, 10
	v_cndmask_b32_e64 v170, 0, 1, s[0:1]
	v_cmp_lt_u32_e64 s[0:1], 27, v4
	v_readlane_b32 s74, v242, 11
	v_readlane_b32 s75, v242, 12
	v_cndmask_b32_e64 v171, 0, 1, s[0:1]
	v_cmp_lt_u32_e64 s[0:1], 28, v4
	v_readlane_b32 s76, v242, 13
	v_readlane_b32 s77, v242, 14
	v_cndmask_b32_e64 v172, 0, 1, s[0:1]
	v_cmp_lt_u32_e64 s[0:1], 29, v4
	v_readlane_b32 s78, v242, 15
	v_readlane_b32 s79, v242, 16
	v_cndmask_b32_e64 v173, 0, 1, s[0:1]
	v_cmp_lt_u32_e64 s[0:1], 30, v4
	v_lshl_add_u64 v[102:103], s[64:65], 0, v[2:3]
	v_readlane_b32 s64, v243, 33
	v_cndmask_b32_e64 v174, 0, 1, s[0:1]
	v_cmp_lt_u32_e64 s[0:1], 31, v4
	s_movk_i32 s30, 0x500
	v_bfe_u32 v194, v218, 3, 3
	v_cndmask_b32_e64 v175, 0, 1, s[0:1]
	v_cmp_lt_u32_e64 s[0:1], 32, v4
	v_readlane_b32 s42, v242, 31
	v_readlane_b32 s65, v243, 34
	v_cndmask_b32_e64 v176, 0, 1, s[0:1]
	v_cmp_lt_u32_e64 s[0:1], 33, v4
	v_readlane_b32 s66, v243, 35
	v_readlane_b32 s67, v243, 36
	v_cndmask_b32_e64 v177, 0, 1, s[0:1]
	v_cmp_lt_u32_e64 s[0:1], 34, v4
	v_readlane_b32 s68, v243, 37
	v_readlane_b32 s78, v243, 47
	v_cndmask_b32_e64 v178, 0, 1, s[0:1]
	v_cmp_lt_u32_e64 s[0:1], 35, v4
	v_readlane_b32 s79, v243, 48
	v_lshl_or_b32 v143, v4, 2, v136
	v_cndmask_b32_e64 v179, 0, 1, s[0:1]
	v_cmp_lt_u32_e64 s[0:1], 36, v4
	v_cmp_eq_u32_e64 s[12:13], 6, v194
	v_cmp_eq_u32_e64 s[14:15], 7, v194
	v_cndmask_b32_e64 v180, 0, 1, s[0:1]
	v_cmp_lt_u32_e64 s[0:1], 37, v4
	v_cmp_eq_u32_e64 s[16:17], 0, v4
	s_lshl_b32 s3, s42, 2
	v_cndmask_b32_e64 v181, 0, 1, s[0:1]
	v_cmp_lt_u32_e64 s[0:1], 38, v4
	v_lshl_add_u64 v[104:105], s[78:79], 0, v[2:3]
	s_mov_b64 s[18:19], 0
	v_cndmask_b32_e64 v182, 0, 1, s[0:1]
	v_cmp_lt_u32_e64 s[0:1], 39, v4
	v_mov_b32_e32 v197, 0xff61b1e6
	s_movk_i32 s31, 0x3f80
	v_cndmask_b32_e64 v183, 0, 1, s[0:1]
	v_cmp_lt_u32_e64 s[0:1], 40, v4
	s_mov_b64 s[20:21], 0x80
	s_waitcnt vmcnt(4)
	v_mov_b32_e32 v198, 0x358637bd
	v_cndmask_b32_e64 v184, 0, 1, s[0:1]
	v_cmp_lt_u32_e64 s[0:1], 41, v4
	s_mov_b32 s35, 0x800000
	s_mov_b32 s54, 0x378e98ab
	v_cndmask_b32_e64 v185, 0, 1, s[0:1]
	v_cmp_lt_u32_e64 s[0:1], 42, v4
	s_mov_b32 s55, 0x3b7cd369
	s_mov_b32 s56, 0xbcc618b2
	v_cndmask_b32_e64 v186, 0, 1, s[0:1]
	v_cmp_lt_u32_e64 s[0:1], 43, v4
	s_mov_b32 s57, 0x3dda74e4
	s_mov_b32 s62, 0x3f228afd
	v_cndmask_b32_e64 v187, 0, 1, s[0:1]
	v_cmp_lt_u32_e64 s[0:1], 44, v4
	s_mov_b32 s63, 0x3e03c728
	s_mov_b32 s64, 0xbfb8aa3b
	v_cndmask_b32_e64 v188, 0, 1, s[0:1]
	v_cmp_lt_u32_e64 s[0:1], 45, v4
	s_mov_b32 s65, 0x42ce8ed0
	s_mov_b32 s66, 0xc2b17218
	v_cndmask_b32_e64 v189, 0, 1, s[0:1]
	v_cmp_lt_u32_e64 s[0:1], 46, v4
	v_mov_b32_e32 v199, 0x3ba10414
	s_brev_b32 s67, -2
	v_cndmask_b32_e64 v190, 0, 1, s[0:1]
	v_cmp_lt_u32_e64 s[0:1], 47, v4
	s_movk_i32 s68, 0x41ff
	v_mov_b32_e32 v200, 0xb9c68948
	v_cndmask_b32_e64 v191, 0, 1, s[0:1]
	v_cmp_lt_u32_e64 s[0:1], 48, v4
	v_mov_b32_e32 v201, 0x7f800000
	v_readlane_b32 s37, v242, 26
	v_cndmask_b32_e64 v192, 0, 1, s[0:1]
	v_cmp_lt_u32_e64 s[0:1], 49, v4
	v_readlane_b32 s40, v242, 29
	v_readlane_b32 s41, v242, 30
	v_cndmask_b32_e64 v193, 0, 1, s[0:1]
	s_mov_b64 s[0:1], 0x1000000
	v_lshl_add_u64 v[108:109], v[106:107], 0, s[0:1]
	s_mov_b64 s[0:1], 0xc0
	v_lshl_add_u64 v[112:113], v[0:1], 0, s[0:1]
	v_add_u32_e32 v0, 32, v100
	v_ashrrev_i32_e32 v1, 31, v0
	v_lshl_add_u64 v[114:115], v[0:1], 2, s[84:85]
	v_mov_b32_e32 v0, 0x120
	v_mad_u32_u24 v196, v214, s30, v0
	v_readlane_b32 s43, v242, 32
	v_readlane_b32 s69, v243, 38
	v_readlane_b32 s70, v243, 39
	v_readlane_b32 s71, v243, 40
	v_readlane_b32 s72, v243, 41
	v_readlane_b32 s73, v243, 42
	v_readlane_b32 s74, v243, 43
	v_readlane_b32 s75, v243, 44
	v_readlane_b32 s76, v243, 45
	v_readlane_b32 s77, v243, 46
	s_mov_b32 s26, 0
	v_readfirstlane_b32 s47, v214
	v_and_b32_e32 v202, 63, v218
	v_mul_u32_u24_e32 v204, 0x3640, v214
	v_lshlrev_b32_e32 v202, 2, v202
	v_add_u32_e32 v204, 0x1400, v204
	v_add_u32_e32 v202, v202, v204
	v_add_u32_e32 v204, 0x3600, v204
	v_mov_b32_e32 v203, 0
	s_branch .LBB0_1117

.LBB0_1117:
	v_ashrrev_i32_e32 v97, 31, v96
	v_lshlrev_b64 v[0:1], 12, v[96:97]
	v_lshl_add_u64 v[116:117], v[102:103], 0, v[0:1]
	s_waitcnt lgkmcnt(0)
	global_load_dwordx4 v[12:15], v[116:117], off
	global_load_dwordx4 v[8:11], v[116:117], off offset:16
	global_load_dwordx4 v[4:7], v[116:117], off offset:32
	global_load_dwordx4 v[0:3], v[116:117], off offset:48
	global_load_dwordx4 v[16:19], v[104:105], off offset:48
	global_load_dwordx4 v[20:23], v[104:105], off offset:32
	global_load_dwordx4 v[24:27], v[104:105], off offset:16
	global_load_dwordx4 v[28:31], v[104:105], off
	v_lshlrev_b64 v[118:119], 10, v[96:97]
	v_lshl_add_u64 v[32:33], s[84:85], 0, v[118:119]
	v_lshl_add_u64 v[34:35], v[100:101], 2, v[32:33]
	v_lshl_add_u64 v[32:33], v[98:99], 2, v[32:33]
	s_mov_b32 s22, 0
	s_mov_b32 s23, 0
	s_cmp_lg_u32 s26, 8
	s_cbranch_scc1 .Lsh_p1
	s_lshl_b32 s22, s47, 8
.Lsh_p1:
	v_lshl_add_u64 v[34:35], v[34:35], 0, s[22:23]
	v_lshl_add_u64 v[32:33], v[32:33], 0, s[22:23]
	global_load_dword v42, v[34:35], off
	global_load_dword v43, v[32:33], off offset:64
	s_mov_b32 s24, 0
	s_cmp_lg_u32 s26, 8
	s_cbranch_scc1 .Lsh_p2
	s_lshl_b32 s24, s47, 5
.Lsh_p2:
	s_waitcnt vmcnt(9)
	v_pk_mul_f32 v[32:33], v[12:13], v[12:13]
	v_pk_mul_f32 v[34:35], v[14:15], v[14:15]
	v_add_f32_e32 v32, v32, v33
	v_add_f32_e32 v32, v32, v34
	s_waitcnt vmcnt(8)
	v_pk_mul_f32 v[36:37], v[8:9], v[8:9]
	v_add_f32_e32 v32, v32, v35
	v_add_f32_e32 v32, v32, v36
	v_pk_mul_f32 v[38:39], v[10:11], v[10:11]
	v_add_f32_e32 v32, v32, v37
	v_add_f32_e32 v32, v32, v38
	s_waitcnt vmcnt(7)
	v_pk_mul_f32 v[40:41], v[4:5], v[4:5]
	v_add_f32_e32 v32, v32, v39
	v_add_f32_e32 v32, v32, v40
	v_pk_mul_f32 v[44:45], v[6:7], v[6:7]
	v_add_f32_e32 v32, v32, v41
	v_add_f32_e32 v32, v32, v44
	s_waitcnt vmcnt(6)
	v_pk_mul_f32 v[46:47], v[0:1], v[0:1]
	v_add_f32_e32 v32, v32, v45
	v_add_f32_e32 v32, v32, v46
	v_pk_mul_f32 v[48:49], v[2:3], v[2:3]
	v_add_f32_e32 v32, v32, v47
	v_add_f32_e32 v32, v32, v48
	v_add_f32_e32 v32, v32, v49
	v_lshl_add_u64 v[36:37], v[112:113], 0, v[118:119]
	v_lshl_add_u64 v[38:39], v[114:115], 0, v[118:119]
	v_lshl_add_u64 v[36:37], v[36:37], 0, s[22:23]
	v_lshl_add_u64 v[38:39], v[38:39], 0, s[22:23]
	s_nop 1
	v_add_f32_dpp v33, v32, v32 quad_perm:[1,0,3,2] row_mask:0xf bank_mask:0xf
	s_nop 1
	v_add_f32_dpp v32, v33, v33 quad_perm:[2,3,0,1] row_mask:0xf bank_mask:0xf
	s_nop 1
	v_add_f32_dpp v33, v32, v32 row_half_mirror row_mask:0xf bank_mask:0xf
	s_nop 1
	v_add_f32_dpp v32, v33, v33 row_mirror row_mask:0xf bank_mask:0xf
	s_nop 1
	v_readlane_b32 s0, v32, 0
	v_readlane_b32 s1, v32, 16
	v_readlane_b32 s22, v32, 32
	v_readlane_b32 s23, v32, 48
	s_nop 1
	v_mov_b32_e32 v72, s0
	v_add_f32_e32 v72, s1, v72
	v_add_f32_e32 v72, s22, v72
	v_add_f32_e32 v72, s23, v72
	v_mov_b32_e32 v73, 0

.Lpf_a_rejoin:
	s_cmp_lg_u32 s26, 8
	s_cbranch_scc1 .Lsh_r1
	s_cmp_eq_u32 s47, 3
	s_cbranch_scc1 .Lsh_r1
	s_lshl_b32 s0, s47, 5
	s_add_i32 s0, s0, 16
	s_cmp_eq_u32 s24, s0
	s_cbranch_scc1 .Lpf_b_rejoin

.Lpf_b_rejoin:
	s_waitcnt lgkmcnt(0)
	v_add_f32_e32 v72, v72, v73
	v_fmamk_f32 v72, v72, 0x3a800000, v198
	v_mul_f32_e32 v73, 0x4b800000, v72
	v_cmp_gt_f32_e32 vcc, s35, v72
	s_nop 1
	v_cndmask_b32_e32 v72, v72, v73, vcc
	v_rsq_f32_e32 v72, v72
	s_nop 0
	v_mul_f32_e32 v73, 0x45800000, v72
	v_cndmask_b32_e32 v72, v72, v73, vcc
	v_mul_f32_e32 v72, 0x3b800000, v72
	v_add_u32_e32 v32, 0x100, v143
	ds_read2st64_b32 v[34:35], v32 offset1:1
	ds_read2st64_b32 v[36:37], v32 offset0:2 offset1:3
	s_lshl_b32 s0, s26, 9
	v_add_u32_e32 v33, s0, v202
	s_lshl_b32 s0, s26, 2
	v_add_u32_e32 v38, s0, v204
	s_waitcnt lgkmcnt(0)
	v_lshlrev_b32_e32 v34, 7, v34
	v_lshlrev_b32_e32 v35, 7, v35
	s_cmp_lg_u32 s26, 8
	s_cbranch_scc1 .Lsh_own
	s_cmp_ge_u32 s47, 2
	s_cselect_b64 vcc, -1, 0
	s_cselect_b32 s22, 0x100, 0
	s_and_b32 s23, s47, 1
	v_and_b32_e32 v53, 63, v218
	v_cndmask_b32_e32 v50, v34, v35, vcc
	v_cndmask_b32_e32 v51, v36, v37, vcc
	v_lshrrev_b32_e32 v52, 5, v53
	v_lshlrev_b32_e32 v53, 2, v53
	v_add_u32_e32 v53, s22, v53
	v_add_u32_e32 v53, 0x2400, v53
	v_cmp_eq_u32_e32 vcc, s23, v52
	s_and_saveexec_b64 s[0:1], vcc
	ds_write_b32 v53, v50 offset:0
	ds_write_b32 v53, v51 offset:4608
	ds_write_b32 v53, v50 offset:13888
	ds_write_b32 v53, v51 offset:18496
	ds_write_b32 v53, v50 offset:27776
	ds_write_b32 v53, v51 offset:32384
	ds_write_b32 v53, v50 offset:41664
	ds_write_b32 v53, v51 offset:46272
	s_mov_b64 exec, s[0:1]
	s_branch .Lsh_done
.Lsh_own:
	ds_write2st64_b32 v33, v34, v35 offset1:1
	ds_write2st64_b32 v33, v36, v37 offset0:18 offset1:19
.Lsh_done:
	ds_write2st64_b32 v33, v203, v203 offset0:36 offset1:37
	ds_write_b32 v38, v72
	s_add_i32 s26, s26, 1
	s_cmp_lt_i32 s26, 8
	s_cbranch_scc0 .Ll1_last
	v_add_u32_e32 v96, s3, v96
	s_branch .LBB0_1117

.Ll1_done:
	s_waitcnt lgkmcnt(0)
	s_barrier
	s_waitcnt lgkmcnt(0)
	v_readlane_b32 s4, v242, 1
	v_readlane_b32 s5, v242, 2
	v_readlane_b32 s6, v243, 47
	v_readlane_b32 s7, v243, 48
	v_readlane_b32 s8, v242, 27
	v_readlane_b32 s9, v242, 28
	v_readlane_b32 s12, v242, 19
	v_readlane_b32 s13, v242, 20
	v_readlane_b32 s14, v243, 6
	v_readlane_b32 s15, v243, 7
	v_readfirstlane_b32 s27, v214
	s_add_i32 s44, s2, 0x4000
	s_add_u32 s10, s8, 0x1000000
	s_addc_u32 s11, s9, 0
	s_mov_b32 s45, s27
	s_lshl_b32 s0, s2, 2
	s_add_i32 s27, s27, s0
	v_and_b32_e32 v188, 7, v218
	v_bfe_u32 v190, v218, 3, 3
	v_lshlrev_b32_e32 v189, 6, v188
	v_lshlrev_b32_e32 v213, 5, v188
	v_lshlrev_b32_e32 v188, 4, v188
	v_lshl_add_u32 v211, v190, 3, v189
	v_lshl_add_u32 v213, v190, 2, v213
	v_bfe_u32 v209, v218, 2, 1
	v_lshlrev_b32_e32 v190, 6, v190
	v_lshlrev_b32_e32 v209, 5, v209
	v_add_u32_e32 v190, v190, v204
	v_add_u32_e32 v190, 0xffffca00, v190
	v_add_u32_e32 v209, v209, v190
	v_add_u32_e32 v209, 0x2400, v209
	s_mov_b32 s38, 0xffff0000
	s_mov_b32 s39, 0xffff0000
	s_mov_b32 s16, 0
